# dead m0 writes removed from the P7/P8/P1 load segments (on top of the P6 and P3 staging changes)
# speedup vs baseline: 1.0016x; 1.0016x over previous
; #define PG8_STAGE(bufoff, gbase, voff) do { _Pragma("unroll") for (int _i = 0; _i < 2; ++_i) \
;         __builtin_amdgcn_global_load_lds((const unsigned*)((const char*)(gbase) + (voff)[_i]), (PG8_LAS unsigned*)(lds + (bufoff) + ldsw + _i * 8192), 16, 0, 0); } while (0)
; #define PG8_LDA(dst, b, h) do { _Pragma("unroll") for (int m = 0; m < 4; ++m) _Pragma("unroll") for (int k = 0; k < 2; ++k) dst[m][k] = *(const PG8_LAS bf16x8*)(lds + PG8_SA(b, h) + aoff + m * 2048 + k * 1024); } while (0)
; #define PG8_LDB(dst, b, h) do { _Pragma("unroll") for (int n = 0; n < 2; ++n) _Pragma("unroll") for (int k = 0; k < 2; ++k) dst[n][k] = *(const PG8_LAS bf16x8*)(lds + PG8_SB(b, h) + boff + n * 2048 + k * 1024); } while (0)
; #define PG8_MMA(ai, bj, At, Bt) do { __builtin_amdgcn_s_setprio(1); _Pragma("unroll") for (int m = 0; m < 4; ++m) _Pragma("unroll") for (int n = 0; n < 2; ++n) _Pragma("unroll") for (int k = 0; k < 2; ++k) \
;         acc[ai][bj][m][n] = __builtin_amdgcn_mfma_f32_16x16x32_bf16(Bt[n][k], At[m][k], acc[ai][bj][m][n], 0, 0, 0); __builtin_amdgcn_s_setprio(0); } while (0)
; #define PG8_WAIT_V(n) asm volatile("s_waitcnt vmcnt(" #n ")" ::: "memory")
; #define PG8_WAIT_L(n) asm volatile("s_waitcnt lgkmcnt(" #n ")" ::: "memory")
; #define PG8_BAR __builtin_amdgcn_s_barrier()
; template <class Epi, class Sched, bool ALIGN_EPI = false, bool SP2 = false>
; __device__ __forceinline__ void gemm_phase(PG8_LAS unsigned char* lds, const Gemm g, const Sched& S, const Epi& E) {
;     ...
;             const char* a1 = cA + (size_t)(t + 1) * kstep;
;             const char* a2 = last ? nA : cA + (size_t)(t + 2) * kstep; const char* b2 = last ? nB : cB + (size_t)(t + 2) * kstep;
;             const char* a3 = a2 + kstep; const char* b3 = b2 + kstep;
;             if (last && has_next) S.a_ready(nxt);
;             if constexpr (SP2) {
;             PG8_LDB(B0, 0, 0); PG8_LDB(B1, 0, 1); PG8_SCHED; PG8_LDA(At, 0, 0); PG8_STAGE(PG8_SA(1, 1), a1 + hstepA, voffA);
;             PG8_WAIT_V(8); PG8_WAIT_L(0); PG8_BAR; PG8_MMA(0, 0, At, B0); PG8_MMA(0, 1, At, B1); PG8_BAR; PG8_SCHED;
;             PG8_LDA(At, 0, 1); PG8_STAGE(PG8_SB(0, 0), b2, voffB); PG8_STAGE(PG8_SB(0, 1), b2 + hstepB, voffB); PG8_STAGE(PG8_SA(0, 0), a2, voffA);
;             PG8_WAIT_V(8); PG8_WAIT_L(0); PG8_BAR; PG8_MMA(1, 0, At, B0); PG8_MMA(1, 1, At, B1); PG8_BAR; PG8_SCHED;
.LBB0_187:
	ds_read_b128 v[128:131], v173
	ds_read_b128 v[132:135], v173 offset:1024
	ds_read_b128 v[152:155], v173 offset:2048
	ds_read_b128 v[156:159], v173 offset:3072
	ds_read_b128 v[160:163], v174
	ds_read_b128 v[164:167], v174 offset:1024
	ds_read_b128 v[180:183], v174 offset:2048
	ds_read_b128 v[184:187], v174 offset:3072
	s_add_u32 s16, s12, 0xfff80080
	s_addc_u32 s17, s13, -1
	s_cmp_eq_u32 s61, 28
	s_cselect_b32 s19, s1, s17
	s_cselect_b32 s18, s26, s16
	s_cselect_b32 s17, s15, s60
	s_cselect_b32 s16, s36, s37
	ds_read_b128 v[188:191], v175
	ds_read_b128 v[192:195], v175 offset:1024
	ds_read_b128 v[196:199], v175 offset:2048
	ds_read_b128 v[200:203], v175 offset:3072
	ds_read_b128 v[204:207], v175 offset:4096
	ds_read_b128 v[208:211], v175 offset:5120
	ds_read_b128 v[212:215], v175 offset:6144
	ds_read_b128 v[216:219], v175 offset:7168
	s_add_u32 s98, s12, 0xfff80000
	s_addc_u32 s99, s13, -1
	s_mov_b32 m0, s7
	s_nop 0
	global_load_lds_dwordx4 v136, s[98:99]
	s_mov_b32 m0, s46
	s_nop 0
	global_load_lds_dwordx4 v140, s[98:99]
	s_add_i32 m0, s77, 0xc000
	s_nop 0
	global_load_lds_dwordx4 v144, s[12:13]
	s_add_i32 m0, s77, 0xe000
	s_nop 0
	global_load_lds_dwordx4 v146, s[12:13]
	s_waitcnt vmcnt(8)
	s_waitcnt lgkmcnt(0)
	s_barrier
	s_setprio 1
	s_waitcnt lgkmcnt(0)
	v_mfma_f32_16x16x32_bf16 v[124:127], v[128:131], v[188:191], v[124:127]
	v_mfma_f32_16x16x32_bf16 v[120:123], v[152:155], v[188:191], v[120:123]
	v_mfma_f32_16x16x32_bf16 v[108:111], v[128:131], v[196:199], v[108:111]
	v_mfma_f32_16x16x32_bf16 v[104:107], v[152:155], v[196:199], v[104:107]
	v_mfma_f32_16x16x32_bf16 v[92:95], v[128:131], v[204:207], v[92:95]
	v_mfma_f32_16x16x32_bf16 v[88:91], v[152:155], v[204:207], v[88:91]
	v_mfma_f32_16x16x32_bf16 v[76:79], v[128:131], v[212:215], v[76:79]
	v_mfma_f32_16x16x32_bf16 v[72:75], v[152:155], v[212:215], v[72:75]
	v_mfma_f32_16x16x32_bf16 v[124:127], v[132:135], v[192:195], v[124:127]
	v_mfma_f32_16x16x32_bf16 v[120:123], v[156:159], v[192:195], v[120:123]
	v_mfma_f32_16x16x32_bf16 v[108:111], v[132:135], v[200:203], v[108:111]
	v_mfma_f32_16x16x32_bf16 v[104:107], v[156:159], v[200:203], v[104:107]
	v_mfma_f32_16x16x32_bf16 v[92:95], v[132:135], v[208:211], v[92:95]
	v_mfma_f32_16x16x32_bf16 v[88:91], v[156:159], v[208:211], v[88:91]
	v_mfma_f32_16x16x32_bf16 v[76:79], v[132:135], v[216:219], v[76:79]
	v_mfma_f32_16x16x32_bf16 v[72:75], v[156:159], v[216:219], v[72:75]
	s_setprio 0
	s_setprio 1
	v_mfma_f32_16x16x32_bf16 v[116:119], v[160:163], v[188:191], v[116:119]
	v_mfma_f32_16x16x32_bf16 v[112:115], v[180:183], v[188:191], v[112:115]
	v_mfma_f32_16x16x32_bf16 v[100:103], v[160:163], v[196:199], v[100:103]
	v_mfma_f32_16x16x32_bf16 v[96:99], v[180:183], v[196:199], v[96:99]
	v_mfma_f32_16x16x32_bf16 v[84:87], v[160:163], v[204:207], v[84:87]
	v_mfma_f32_16x16x32_bf16 v[80:83], v[180:183], v[204:207], v[80:83]
	v_mfma_f32_16x16x32_bf16 v[68:71], v[160:163], v[212:215], v[68:71]
	v_mfma_f32_16x16x32_bf16 v[64:67], v[180:183], v[212:215], v[64:67]
	v_mfma_f32_16x16x32_bf16 v[116:119], v[164:167], v[192:195], v[116:119]
	v_mfma_f32_16x16x32_bf16 v[112:115], v[184:187], v[192:195], v[112:115]
	v_mfma_f32_16x16x32_bf16 v[100:103], v[164:167], v[200:203], v[100:103]
	v_mfma_f32_16x16x32_bf16 v[96:99], v[184:187], v[200:203], v[96:99]
	v_mfma_f32_16x16x32_bf16 v[84:87], v[164:167], v[208:211], v[84:87]
	v_mfma_f32_16x16x32_bf16 v[80:83], v[184:187], v[208:211], v[80:83]
	v_mfma_f32_16x16x32_bf16 v[68:71], v[164:167], v[216:219], v[68:71]
	v_mfma_f32_16x16x32_bf16 v[64:67], v[184:187], v[216:219], v[64:67]
	s_setprio 0
	s_barrier
	s_add_i32 s69, s47, s33
	s_mov_b32 m0, s69
	ds_read_b128 v[188:191], v175 offset:16384
	ds_read_b128 v[192:195], v175 offset:17408
	ds_read_b128 v[196:199], v175 offset:18432
	ds_read_b128 v[200:203], v175 offset:19456
	ds_read_b128 v[204:207], v175 offset:20480
	ds_read_b128 v[208:211], v175 offset:21504
	ds_read_b128 v[212:215], v175 offset:22528
	ds_read_b128 v[216:219], v175 offset:23552
	global_load_lds_dwordx4 v138, s[16:17]
	s_add_i32 m0, s69, 0x2000
	s_add_u32 s70, s16, 0x80000
	s_addc_u32 s71, s17, 0
	s_add_i32 s69, s56, s33
	global_load_lds_dwordx4 v142, s[16:17]
	s_mov_b32 m0, s69
	s_nop 0
	global_load_lds_dwordx4 v138, s[70:71]
	s_add_i32 m0, s69, 0x2000
	s_nop 0
	global_load_lds_dwordx4 v142, s[70:71]
	s_waitcnt vmcnt(6)
	s_waitcnt lgkmcnt(0)
	s_barrier
	s_setprio 1
	s_waitcnt lgkmcnt(0)
	v_mfma_f32_16x16x32_bf16 v[60:63], v[128:131], v[188:191], v[60:63]
	v_mfma_f32_16x16x32_bf16 v[56:59], v[152:155], v[188:191], v[56:59]
	v_mfma_f32_16x16x32_bf16 v[44:47], v[128:131], v[196:199], v[44:47]
	v_mfma_f32_16x16x32_bf16 v[40:43], v[152:155], v[196:199], v[40:43]
	v_mfma_f32_16x16x32_bf16 v[28:31], v[128:131], v[204:207], v[28:31]
	v_mfma_f32_16x16x32_bf16 v[24:27], v[152:155], v[204:207], v[24:27]
	v_mfma_f32_16x16x32_bf16 v[12:15], v[128:131], v[212:215], v[12:15]
	v_mfma_f32_16x16x32_bf16 v[8:11], v[152:155], v[212:215], v[8:11]
	v_mfma_f32_16x16x32_bf16 v[60:63], v[132:135], v[192:195], v[60:63]
	v_mfma_f32_16x16x32_bf16 v[56:59], v[156:159], v[192:195], v[56:59]
	v_mfma_f32_16x16x32_bf16 v[44:47], v[132:135], v[200:203], v[44:47]
	v_mfma_f32_16x16x32_bf16 v[40:43], v[156:159], v[200:203], v[40:43]
	v_mfma_f32_16x16x32_bf16 v[28:31], v[132:135], v[208:211], v[28:31]
	v_mfma_f32_16x16x32_bf16 v[24:27], v[156:159], v[208:211], v[24:27]
	v_mfma_f32_16x16x32_bf16 v[12:15], v[132:135], v[216:219], v[12:15]
	v_mfma_f32_16x16x32_bf16 v[8:11], v[156:159], v[216:219], v[8:11]
	s_setprio 0
	s_setprio 1
	v_mfma_f32_16x16x32_bf16 v[52:55], v[160:163], v[188:191], v[52:55]
	v_mfma_f32_16x16x32_bf16 v[48:51], v[180:183], v[188:191], v[48:51]
	v_mfma_f32_16x16x32_bf16 v[36:39], v[160:163], v[196:199], v[36:39]
	v_mfma_f32_16x16x32_bf16 v[32:35], v[180:183], v[196:199], v[32:35]
	v_mfma_f32_16x16x32_bf16 v[20:23], v[160:163], v[204:207], v[20:23]
	v_mfma_f32_16x16x32_bf16 v[16:19], v[180:183], v[204:207], v[16:19]
	v_mfma_f32_16x16x32_bf16 v[4:7], v[160:163], v[212:215], v[4:7]
	v_mfma_f32_16x16x32_bf16 v[0:3], v[180:183], v[212:215], v[0:3]
	v_mfma_f32_16x16x32_bf16 v[52:55], v[164:167], v[192:195], v[52:55]
	v_mfma_f32_16x16x32_bf16 v[48:51], v[184:187], v[192:195], v[48:51]
	v_mfma_f32_16x16x32_bf16 v[36:39], v[164:167], v[200:203], v[36:39]
	v_mfma_f32_16x16x32_bf16 v[32:35], v[184:187], v[200:203], v[32:35]
	v_mfma_f32_16x16x32_bf16 v[20:23], v[164:167], v[208:211], v[20:23]
	v_mfma_f32_16x16x32_bf16 v[16:19], v[184:187], v[208:211], v[16:19]
	v_mfma_f32_16x16x32_bf16 v[4:7], v[164:167], v[216:219], v[4:7]
	v_mfma_f32_16x16x32_bf16 v[0:3], v[184:187], v[216:219], v[0:3]
	s_setprio 0
	s_barrier
; #define PG8_STAGE(bufoff, gbase, voff) do { _Pragma("unroll") for (int _i = 0; _i < 2; ++_i) \
;         __builtin_amdgcn_global_load_lds((const unsigned*)((const char*)(gbase) + (voff)[_i]), (PG8_LAS unsigned*)(lds + (bufoff) + ldsw + _i * 8192), 16, 0, 0); } while (0)
; #define PG8_LDA(dst, b, h) do { _Pragma("unroll") for (int m = 0; m < 4; ++m) _Pragma("unroll") for (int k = 0; k < 2; ++k) dst[m][k] = *(const PG8_LAS bf16x8*)(lds + PG8_SA(b, h) + aoff + m * 2048 + k * 1024); } while (0)
; #define PG8_LDB(dst, b, h) do { _Pragma("unroll") for (int n = 0; n < 2; ++n) _Pragma("unroll") for (int k = 0; k < 2; ++k) dst[n][k] = *(const PG8_LAS bf16x8*)(lds + PG8_SB(b, h) + boff + n * 2048 + k * 1024); } while (0)
; #define PG8_MMA(ai, bj, At, Bt) do { __builtin_amdgcn_s_setprio(1); _Pragma("unroll") for (int m = 0; m < 4; ++m) _Pragma("unroll") for (int n = 0; n < 2; ++n) _Pragma("unroll") for (int k = 0; k < 2; ++k) \
;         acc[ai][bj][m][n] = __builtin_amdgcn_mfma_f32_16x16x32_bf16(Bt[n][k], At[m][k], acc[ai][bj][m][n], 0, 0, 0); __builtin_amdgcn_s_setprio(0); } while (0)
; #define PG8_WAIT_V(n) asm volatile("s_waitcnt vmcnt(" #n ")" ::: "memory")
; #define PG8_WAIT_L(n) asm volatile("s_waitcnt lgkmcnt(" #n ")" ::: "memory")
; #define PG8_BAR __builtin_amdgcn_s_barrier()
; #define PG8_SCHED __builtin_amdgcn_sched_barrier(0)
; template <class Epi, class Sched, bool ALIGN_EPI = false, bool SP2 = false>
; __device__ __forceinline__ void gemm_phase(PG8_LAS unsigned char* lds, const Gemm g, const Sched& S, const Epi& E) {
;     ...
;             PG8_LDB(B0, 1, 0); PG8_LDB(B1, 1, 1); PG8_SCHED; PG8_LDA(At, 1, 0); PG8_STAGE(PG8_SA(0, 1), a2 + hstepA, voffA);
;             PG8_WAIT_V(8); PG8_WAIT_L(0); PG8_BAR; PG8_MMA(0, 0, At, B0); PG8_MMA(0, 1, At, B1); PG8_BAR; PG8_SCHED;
;             PG8_LDA(At, 1, 1); PG8_STAGE(PG8_SB(1, 0), b3, voffB); PG8_STAGE(PG8_SB(1, 1), b3 + hstepB, voffB); PG8_STAGE(PG8_SA(1, 0), a3, voffA);
;             PG8_WAIT_V(8); PG8_WAIT_L(0); PG8_BAR; PG8_MMA(1, 0, At, B0); PG8_MMA(1, 1, At, B1); PG8_BAR; PG8_SCHED;
	s_add_i32 s69, 0, 0x18000
	s_add_i32 s70, 0, 0x1c000
	v_add_u32_e32 v156, s69, v172
	v_add_u32_e32 v179, s70, v172
	ds_read_b128 v[128:131], v156
	ds_read_b128 v[132:135], v156 offset:1024
	ds_read_b128 v[152:155], v156 offset:2048
	ds_read_b128 v[156:159], v156 offset:3072
	ds_read_b128 v[160:163], v179
	ds_read_b128 v[164:167], v179 offset:1024
	ds_read_b128 v[180:183], v179 offset:2048
	ds_read_b128 v[184:187], v179 offset:3072
	s_mov_b64 s[100:101], s[18:19]
	s_add_u32 s18, s18, 0x80000
	s_addc_u32 s19, s19, 0
	ds_read_b128 v[188:191], v175 offset:32768
	ds_read_b128 v[192:195], v175 offset:33792
	ds_read_b128 v[196:199], v175 offset:34816
	ds_read_b128 v[200:203], v175 offset:35840
	ds_read_b128 v[204:207], v175 offset:36864
	ds_read_b128 v[208:211], v175 offset:37888
	ds_read_b128 v[212:215], v175 offset:38912
	ds_read_b128 v[216:219], v175 offset:39936
	s_mov_b32 m0, s77
	s_nop 0
	global_load_lds_dwordx4 v136, s[100:101]
	s_mov_b32 m0, s22
	s_nop 0
	global_load_lds_dwordx4 v140, s[100:101]
	s_mov_b32 m0, s23
	s_nop 0
	global_load_lds_dwordx4 v136, s[18:19]
	s_mov_b32 m0, s4
	s_nop 0
	global_load_lds_dwordx4 v140, s[18:19]
	s_waitcnt vmcnt(8)
	s_waitcnt lgkmcnt(0)
	s_barrier
	s_setprio 1
	s_waitcnt lgkmcnt(0)
	v_mfma_f32_16x16x32_bf16 v[124:127], v[128:131], v[188:191], v[124:127]
	v_mfma_f32_16x16x32_bf16 v[120:123], v[152:155], v[188:191], v[120:123]
	v_mfma_f32_16x16x32_bf16 v[108:111], v[128:131], v[196:199], v[108:111]
	v_mfma_f32_16x16x32_bf16 v[104:107], v[152:155], v[196:199], v[104:107]
	v_mfma_f32_16x16x32_bf16 v[92:95], v[128:131], v[204:207], v[92:95]
	v_mfma_f32_16x16x32_bf16 v[88:91], v[152:155], v[204:207], v[88:91]
	v_mfma_f32_16x16x32_bf16 v[76:79], v[128:131], v[212:215], v[76:79]
	v_mfma_f32_16x16x32_bf16 v[72:75], v[152:155], v[212:215], v[72:75]
	v_mfma_f32_16x16x32_bf16 v[124:127], v[132:135], v[192:195], v[124:127]
	v_mfma_f32_16x16x32_bf16 v[120:123], v[156:159], v[192:195], v[120:123]
	v_mfma_f32_16x16x32_bf16 v[108:111], v[132:135], v[200:203], v[108:111]
	v_mfma_f32_16x16x32_bf16 v[104:107], v[156:159], v[200:203], v[104:107]
	v_mfma_f32_16x16x32_bf16 v[92:95], v[132:135], v[208:211], v[92:95]
	v_mfma_f32_16x16x32_bf16 v[88:91], v[156:159], v[208:211], v[88:91]
	v_mfma_f32_16x16x32_bf16 v[76:79], v[132:135], v[216:219], v[76:79]
	v_mfma_f32_16x16x32_bf16 v[72:75], v[156:159], v[216:219], v[72:75]
	s_setprio 0
	s_setprio 1
	v_mfma_f32_16x16x32_bf16 v[116:119], v[160:163], v[188:191], v[116:119]
	v_mfma_f32_16x16x32_bf16 v[112:115], v[180:183], v[188:191], v[112:115]
	v_mfma_f32_16x16x32_bf16 v[100:103], v[160:163], v[196:199], v[100:103]
	v_mfma_f32_16x16x32_bf16 v[96:99], v[180:183], v[196:199], v[96:99]
	v_mfma_f32_16x16x32_bf16 v[84:87], v[160:163], v[204:207], v[84:87]
	v_mfma_f32_16x16x32_bf16 v[80:83], v[180:183], v[204:207], v[80:83]
	v_mfma_f32_16x16x32_bf16 v[68:71], v[160:163], v[212:215], v[68:71]
	v_mfma_f32_16x16x32_bf16 v[64:67], v[180:183], v[212:215], v[64:67]
	v_mfma_f32_16x16x32_bf16 v[116:119], v[164:167], v[192:195], v[116:119]
	v_mfma_f32_16x16x32_bf16 v[112:115], v[184:187], v[192:195], v[112:115]
	v_mfma_f32_16x16x32_bf16 v[100:103], v[164:167], v[200:203], v[100:103]
	v_mfma_f32_16x16x32_bf16 v[96:99], v[184:187], v[200:203], v[96:99]
	v_mfma_f32_16x16x32_bf16 v[84:87], v[164:167], v[208:211], v[84:87]
	v_mfma_f32_16x16x32_bf16 v[80:83], v[184:187], v[208:211], v[80:83]
	v_mfma_f32_16x16x32_bf16 v[68:71], v[164:167], v[216:219], v[68:71]
	v_mfma_f32_16x16x32_bf16 v[64:67], v[184:187], v[216:219], v[64:67]
	s_setprio 0
	s_barrier
	s_add_i32 s18, s69, s33
	s_add_u32 s98, s16, 0x80
	s_addc_u32 s99, s17, 0
	s_mov_b32 m0, s18
	ds_read_b128 v[188:191], v175 offset:49152
	ds_read_b128 v[192:195], v175 offset:50176
	ds_read_b128 v[196:199], v175 offset:51200
	ds_read_b128 v[200:203], v175 offset:52224
	ds_read_b128 v[204:207], v175 offset:53248
	ds_read_b128 v[208:211], v175 offset:54272
	ds_read_b128 v[212:215], v175 offset:55296
	ds_read_b128 v[216:219], v175 offset:56320
	global_load_lds_dwordx4 v138, s[98:99]
	s_add_i32 m0, s18, 0x2000
	s_add_u32 s16, s16, 0x80080
	s_addc_u32 s17, s17, 0
	s_add_i32 s18, s70, s33
	global_load_lds_dwordx4 v142, s[98:99]
	s_mov_b32 m0, s18
	s_nop 0
	global_load_lds_dwordx4 v138, s[16:17]
	s_add_i32 m0, s18, 0x2000
	s_nop 0
	global_load_lds_dwordx4 v142, s[16:17]
	s_waitcnt vmcnt(6)
	s_waitcnt lgkmcnt(0)
	s_barrier
	s_setprio 1
	s_waitcnt lgkmcnt(0)
	v_mfma_f32_16x16x32_bf16 v[60:63], v[128:131], v[188:191], v[60:63]
	v_mfma_f32_16x16x32_bf16 v[56:59], v[152:155], v[188:191], v[56:59]
	v_mfma_f32_16x16x32_bf16 v[44:47], v[128:131], v[196:199], v[44:47]
	v_mfma_f32_16x16x32_bf16 v[40:43], v[152:155], v[196:199], v[40:43]
	v_mfma_f32_16x16x32_bf16 v[28:31], v[128:131], v[204:207], v[28:31]
	v_mfma_f32_16x16x32_bf16 v[24:27], v[152:155], v[204:207], v[24:27]
	v_mfma_f32_16x16x32_bf16 v[12:15], v[128:131], v[212:215], v[12:15]
	v_mfma_f32_16x16x32_bf16 v[8:11], v[152:155], v[212:215], v[8:11]
	v_mfma_f32_16x16x32_bf16 v[60:63], v[132:135], v[192:195], v[60:63]
	v_mfma_f32_16x16x32_bf16 v[56:59], v[156:159], v[192:195], v[56:59]
	v_mfma_f32_16x16x32_bf16 v[44:47], v[132:135], v[200:203], v[44:47]
	v_mfma_f32_16x16x32_bf16 v[40:43], v[156:159], v[200:203], v[40:43]
	v_mfma_f32_16x16x32_bf16 v[28:31], v[132:135], v[208:211], v[28:31]
	v_mfma_f32_16x16x32_bf16 v[24:27], v[156:159], v[208:211], v[24:27]
	v_mfma_f32_16x16x32_bf16 v[12:15], v[132:135], v[216:219], v[12:15]
	v_mfma_f32_16x16x32_bf16 v[8:11], v[156:159], v[216:219], v[8:11]
	s_setprio 0
	s_setprio 1
	v_mfma_f32_16x16x32_bf16 v[52:55], v[160:163], v[188:191], v[52:55]
	v_mfma_f32_16x16x32_bf16 v[48:51], v[180:183], v[188:191], v[48:51]
	v_mfma_f32_16x16x32_bf16 v[36:39], v[160:163], v[196:199], v[36:39]
	v_mfma_f32_16x16x32_bf16 v[32:35], v[180:183], v[196:199], v[32:35]
	v_mfma_f32_16x16x32_bf16 v[20:23], v[160:163], v[204:207], v[20:23]
	v_mfma_f32_16x16x32_bf16 v[16:19], v[180:183], v[204:207], v[16:19]
	v_mfma_f32_16x16x32_bf16 v[4:7], v[160:163], v[212:215], v[4:7]
	v_mfma_f32_16x16x32_bf16 v[0:3], v[180:183], v[212:215], v[0:3]
	v_mfma_f32_16x16x32_bf16 v[52:55], v[164:167], v[192:195], v[52:55]
	v_mfma_f32_16x16x32_bf16 v[48:51], v[184:187], v[192:195], v[48:51]
	v_mfma_f32_16x16x32_bf16 v[36:39], v[164:167], v[200:203], v[36:39]
	v_mfma_f32_16x16x32_bf16 v[32:35], v[184:187], v[200:203], v[32:35]
	v_mfma_f32_16x16x32_bf16 v[20:23], v[164:167], v[208:211], v[20:23]
	v_mfma_f32_16x16x32_bf16 v[16:19], v[184:187], v[208:211], v[16:19]
	v_mfma_f32_16x16x32_bf16 v[4:7], v[164:167], v[216:219], v[4:7]
	v_mfma_f32_16x16x32_bf16 v[0:3], v[184:187], v[216:219], v[0:3]
	s_setprio 0
	s_barrier
	s_add_i32 s61, s61, 2
	s_add_u32 s12, s12, 0x100
	s_addc_u32 s13, s13, 0
	s_add_u32 s37, s37, 0x100
	s_addc_u32 s60, s60, 0
	s_cmp_gt_u32 s61, 29
	s_cbranch_scc0 .LBB0_187
	s_and_b64 vcc, exec, s[96:97]
	s_cbranch_vccz .LBB0_190
	s_barrier

; #define PG8_STAGE(bufoff, gbase, voff) do { _Pragma("unroll") for (int _i = 0; _i < 2; ++_i) \
;         __builtin_amdgcn_global_load_lds((const unsigned*)((const char*)(gbase) + (voff)[_i]), (PG8_LAS unsigned*)(lds + (bufoff) + ldsw + _i * 8192), 16, 0, 0); } while (0)
; #define PG8_LDA(dst, b, h) do { _Pragma("unroll") for (int m = 0; m < 4; ++m) _Pragma("unroll") for (int k = 0; k < 2; ++k) dst[m][k] = *(const PG8_LAS bf16x8*)(lds + PG8_SA(b, h) + aoff + m * 2048 + k * 1024); } while (0)
; #define PG8_LDB(dst, b, h) do { _Pragma("unroll") for (int n = 0; n < 2; ++n) _Pragma("unroll") for (int k = 0; k < 2; ++k) dst[n][k] = *(const PG8_LAS bf16x8*)(lds + PG8_SB(b, h) + boff + n * 2048 + k * 1024); } while (0)
; #define PG8_MMA(ai, bj, At, Bt) do { __builtin_amdgcn_s_setprio(1); _Pragma("unroll") for (int m = 0; m < 4; ++m) _Pragma("unroll") for (int n = 0; n < 2; ++n) _Pragma("unroll") for (int k = 0; k < 2; ++k) \
;         acc[ai][bj][m][n] = __builtin_amdgcn_mfma_f32_16x16x32_bf16(Bt[n][k], At[m][k], acc[ai][bj][m][n], 0, 0, 0); __builtin_amdgcn_s_setprio(0); } while (0)
; #define PG8_WAIT_V(n) asm volatile("s_waitcnt vmcnt(" #n ")" ::: "memory")
; #define PG8_WAIT_L(n) asm volatile("s_waitcnt lgkmcnt(" #n ")" ::: "memory")
; #define PG8_BAR __builtin_amdgcn_s_barrier()
; template <class Epi, class Sched, bool ALIGN_EPI = false, bool SP2 = false>
; __device__ __forceinline__ void gemm_phase(PG8_LAS unsigned char* lds, const Gemm g, const Sched& S, const Epi& E) {
;     ...
;             const char* a1 = cA + (size_t)(t + 1) * kstep;
;             const char* a2 = last ? nA : cA + (size_t)(t + 2) * kstep; const char* b2 = last ? nB : cB + (size_t)(t + 2) * kstep;
;             const char* a3 = a2 + kstep; const char* b3 = b2 + kstep;
;             if (last && has_next) S.a_ready(nxt);
;             if constexpr (SP2) {
;             PG8_LDB(B0, 0, 0); PG8_LDB(B1, 0, 1); PG8_SCHED; PG8_LDA(At, 0, 0); PG8_STAGE(PG8_SA(1, 1), a1 + hstepA, voffA);
;             PG8_WAIT_V(8); PG8_WAIT_L(0); PG8_BAR; PG8_MMA(0, 0, At, B0); PG8_MMA(0, 1, At, B1); PG8_BAR; PG8_SCHED;
;             PG8_LDA(At, 0, 1); PG8_STAGE(PG8_SB(0, 0), b2, voffB); PG8_STAGE(PG8_SB(0, 1), b2 + hstepB, voffB); PG8_STAGE(PG8_SA(0, 0), a2, voffA);
;             PG8_WAIT_V(8); PG8_WAIT_L(0); PG8_BAR; PG8_MMA(1, 0, At, B0); PG8_MMA(1, 1, At, B1); PG8_BAR; PG8_SCHED;
.Lp7_full_loop:
.LBB0_1824:
	ds_read_b128 v[144:147], v151
	ds_read_b128 v[156:159], v151 offset:1024
	ds_read_b128 v[160:163], v151 offset:2048
	ds_read_b128 v[164:167], v151 offset:3072
	ds_read_b128 v[168:171], v152
	ds_read_b128 v[172:175], v152 offset:1024
	ds_read_b128 v[176:179], v152 offset:2048
	ds_read_b128 v[180:183], v152 offset:3072
	s_add_u32 s34, s30, 0xfff80080
	s_addc_u32 s35, s31, -1
	s_cmp_eq_u32 s62, 28
	s_cselect_b32 s39, s21, s35
	s_cselect_b32 s38, s25, s34
	s_cselect_b32 s35, s23, s61
	s_cselect_b32 s34, s59, s60
	ds_read_b128 v[184:187], v153
	ds_read_b128 v[188:191], v153 offset:1024
	ds_read_b128 v[192:195], v153 offset:2048
	ds_read_b128 v[196:199], v153 offset:3072
	ds_read_b128 v[200:203], v153 offset:4096
	ds_read_b128 v[204:207], v153 offset:5120
	ds_read_b128 v[208:211], v153 offset:6144
	ds_read_b128 v[212:215], v153 offset:7168
	s_add_u32 s98, s30, 0xfff80000
	s_addc_u32 s99, s31, -1
	s_mov_b32 m0, s46
	s_nop 0
	global_load_lds_dwordx4 v134, s[98:99]
	s_mov_b32 m0, s47
	s_nop 0
	global_load_lds_dwordx4 v130, s[98:99]
	s_add_i32 m0, s6, 0xc000
	s_nop 0
	global_load_lds_dwordx4 v136, s[30:31]
	s_add_i32 m0, s6, 0xe000
	s_nop 0
	global_load_lds_dwordx4 v138, s[30:31]
	s_waitcnt vmcnt(8)
	s_waitcnt lgkmcnt(0)
	s_barrier
	s_setprio 1
	s_waitcnt lgkmcnt(0)
	v_mfma_f32_16x16x32_bf16 v[124:127], v[144:147], v[184:187], v[124:127]
	v_mfma_f32_16x16x32_bf16 v[116:119], v[160:163], v[184:187], v[116:119]
	v_mfma_f32_16x16x32_bf16 v[108:111], v[144:147], v[192:195], v[108:111]
	v_mfma_f32_16x16x32_bf16 v[100:103], v[160:163], v[192:195], v[100:103]
	v_mfma_f32_16x16x32_bf16 v[92:95], v[144:147], v[200:203], v[92:95]
	v_mfma_f32_16x16x32_bf16 v[84:87], v[160:163], v[200:203], v[84:87]
	v_mfma_f32_16x16x32_bf16 v[76:79], v[144:147], v[208:211], v[76:79]
	v_mfma_f32_16x16x32_bf16 v[68:71], v[160:163], v[208:211], v[68:71]
	v_mfma_f32_16x16x32_bf16 v[124:127], v[156:159], v[188:191], v[124:127]
	v_mfma_f32_16x16x32_bf16 v[116:119], v[164:167], v[188:191], v[116:119]
	v_mfma_f32_16x16x32_bf16 v[108:111], v[156:159], v[196:199], v[108:111]
	v_mfma_f32_16x16x32_bf16 v[100:103], v[164:167], v[196:199], v[100:103]
	v_mfma_f32_16x16x32_bf16 v[92:95], v[156:159], v[204:207], v[92:95]
	v_mfma_f32_16x16x32_bf16 v[84:87], v[164:167], v[204:207], v[84:87]
	v_mfma_f32_16x16x32_bf16 v[76:79], v[156:159], v[212:215], v[76:79]
	v_mfma_f32_16x16x32_bf16 v[68:71], v[164:167], v[212:215], v[68:71]
	s_setprio 0
	s_setprio 1
	v_mfma_f32_16x16x32_bf16 v[120:123], v[168:171], v[184:187], v[120:123]
	v_mfma_f32_16x16x32_bf16 v[112:115], v[176:179], v[184:187], v[112:115]
	v_mfma_f32_16x16x32_bf16 v[104:107], v[168:171], v[192:195], v[104:107]
	v_mfma_f32_16x16x32_bf16 v[96:99], v[176:179], v[192:195], v[96:99]
	v_mfma_f32_16x16x32_bf16 v[88:91], v[168:171], v[200:203], v[88:91]
	v_mfma_f32_16x16x32_bf16 v[80:83], v[176:179], v[200:203], v[80:83]
	v_mfma_f32_16x16x32_bf16 v[72:75], v[168:171], v[208:211], v[72:75]
	v_mfma_f32_16x16x32_bf16 v[64:67], v[176:179], v[208:211], v[64:67]
	v_mfma_f32_16x16x32_bf16 v[120:123], v[172:175], v[188:191], v[120:123]
	v_mfma_f32_16x16x32_bf16 v[112:115], v[180:183], v[188:191], v[112:115]
	v_mfma_f32_16x16x32_bf16 v[104:107], v[172:175], v[196:199], v[104:107]
	v_mfma_f32_16x16x32_bf16 v[96:99], v[180:183], v[196:199], v[96:99]
	v_mfma_f32_16x16x32_bf16 v[88:91], v[172:175], v[204:207], v[88:91]
	v_mfma_f32_16x16x32_bf16 v[80:83], v[180:183], v[204:207], v[80:83]
	v_mfma_f32_16x16x32_bf16 v[72:75], v[172:175], v[212:215], v[72:75]
	v_mfma_f32_16x16x32_bf16 v[64:67], v[180:183], v[212:215], v[64:67]
	s_setprio 0
	s_barrier
	s_add_i32 s63, s53, s4
	s_mov_b32 m0, s63
	ds_read_b128 v[184:187], v153 offset:16384
	ds_read_b128 v[188:191], v153 offset:17408
	ds_read_b128 v[192:195], v153 offset:18432
	ds_read_b128 v[196:199], v153 offset:19456
	ds_read_b128 v[200:203], v153 offset:20480
	ds_read_b128 v[204:207], v153 offset:21504
	ds_read_b128 v[208:211], v153 offset:22528
	ds_read_b128 v[212:215], v153 offset:23552
	global_load_lds_dwordx4 v132, s[34:35]
	s_add_i32 m0, s63, 0x2000
	s_add_u32 s64, s34, 0x80000
	s_addc_u32 s65, s35, 0
	s_add_i32 s63, s54, s4
	global_load_lds_dwordx4 v128, s[34:35]
	s_mov_b32 m0, s63
	s_nop 0
	global_load_lds_dwordx4 v132, s[64:65]
	s_add_i32 m0, s63, 0x2000
	s_nop 0
	global_load_lds_dwordx4 v128, s[64:65]
	s_waitcnt vmcnt(6)
	s_waitcnt lgkmcnt(0)
	s_barrier
	s_setprio 1
	s_waitcnt lgkmcnt(0)
	v_mfma_f32_16x16x32_bf16 v[60:63], v[144:147], v[184:187], v[60:63]
	v_mfma_f32_16x16x32_bf16 v[52:55], v[160:163], v[184:187], v[52:55]
	v_mfma_f32_16x16x32_bf16 v[44:47], v[144:147], v[192:195], v[44:47]
	v_mfma_f32_16x16x32_bf16 v[36:39], v[160:163], v[192:195], v[36:39]
	v_mfma_f32_16x16x32_bf16 v[28:31], v[144:147], v[200:203], v[28:31]
	v_mfma_f32_16x16x32_bf16 v[20:23], v[160:163], v[200:203], v[20:23]
	v_mfma_f32_16x16x32_bf16 v[12:15], v[144:147], v[208:211], v[12:15]
	v_mfma_f32_16x16x32_bf16 v[4:7], v[160:163], v[208:211], v[4:7]
	v_mfma_f32_16x16x32_bf16 v[60:63], v[156:159], v[188:191], v[60:63]
	v_mfma_f32_16x16x32_bf16 v[52:55], v[164:167], v[188:191], v[52:55]
	v_mfma_f32_16x16x32_bf16 v[44:47], v[156:159], v[196:199], v[44:47]
	v_mfma_f32_16x16x32_bf16 v[36:39], v[164:167], v[196:199], v[36:39]
	v_mfma_f32_16x16x32_bf16 v[28:31], v[156:159], v[204:207], v[28:31]
	v_mfma_f32_16x16x32_bf16 v[20:23], v[164:167], v[204:207], v[20:23]
	v_mfma_f32_16x16x32_bf16 v[12:15], v[156:159], v[212:215], v[12:15]
	v_mfma_f32_16x16x32_bf16 v[4:7], v[164:167], v[212:215], v[4:7]
	s_setprio 0
	s_setprio 1
	v_mfma_f32_16x16x32_bf16 v[56:59], v[168:171], v[184:187], v[56:59]
	v_mfma_f32_16x16x32_bf16 v[48:51], v[176:179], v[184:187], v[48:51]
	v_mfma_f32_16x16x32_bf16 v[40:43], v[168:171], v[192:195], v[40:43]
	v_mfma_f32_16x16x32_bf16 v[32:35], v[176:179], v[192:195], v[32:35]
	v_mfma_f32_16x16x32_bf16 v[24:27], v[168:171], v[200:203], v[24:27]
	v_mfma_f32_16x16x32_bf16 v[16:19], v[176:179], v[200:203], v[16:19]
	v_mfma_f32_16x16x32_bf16 v[8:11], v[168:171], v[208:211], v[8:11]
	v_mfma_f32_16x16x32_bf16 v[0:3], v[176:179], v[208:211], v[0:3]
	v_mfma_f32_16x16x32_bf16 v[56:59], v[172:175], v[188:191], v[56:59]
	v_mfma_f32_16x16x32_bf16 v[48:51], v[180:183], v[188:191], v[48:51]
	v_mfma_f32_16x16x32_bf16 v[40:43], v[172:175], v[196:199], v[40:43]
	v_mfma_f32_16x16x32_bf16 v[32:35], v[180:183], v[196:199], v[32:35]
	v_mfma_f32_16x16x32_bf16 v[24:27], v[172:175], v[204:207], v[24:27]
	v_mfma_f32_16x16x32_bf16 v[16:19], v[180:183], v[204:207], v[16:19]
	v_mfma_f32_16x16x32_bf16 v[8:11], v[172:175], v[212:215], v[8:11]
	v_mfma_f32_16x16x32_bf16 v[0:3], v[180:183], v[212:215], v[0:3]
	s_setprio 0
	s_barrier
; #define PG8_STAGE(bufoff, gbase, voff) do { _Pragma("unroll") for (int _i = 0; _i < 2; ++_i) \
;         __builtin_amdgcn_global_load_lds((const unsigned*)((const char*)(gbase) + (voff)[_i]), (PG8_LAS unsigned*)(lds + (bufoff) + ldsw + _i * 8192), 16, 0, 0); } while (0)
; #define PG8_LDA(dst, b, h) do { _Pragma("unroll") for (int m = 0; m < 4; ++m) _Pragma("unroll") for (int k = 0; k < 2; ++k) dst[m][k] = *(const PG8_LAS bf16x8*)(lds + PG8_SA(b, h) + aoff + m * 2048 + k * 1024); } while (0)
; #define PG8_LDB(dst, b, h) do { _Pragma("unroll") for (int n = 0; n < 2; ++n) _Pragma("unroll") for (int k = 0; k < 2; ++k) dst[n][k] = *(const PG8_LAS bf16x8*)(lds + PG8_SB(b, h) + boff + n * 2048 + k * 1024); } while (0)
; #define PG8_MMA(ai, bj, At, Bt) do { __builtin_amdgcn_s_setprio(1); _Pragma("unroll") for (int m = 0; m < 4; ++m) _Pragma("unroll") for (int n = 0; n < 2; ++n) _Pragma("unroll") for (int k = 0; k < 2; ++k) \
;         acc[ai][bj][m][n] = __builtin_amdgcn_mfma_f32_16x16x32_bf16(Bt[n][k], At[m][k], acc[ai][bj][m][n], 0, 0, 0); __builtin_amdgcn_s_setprio(0); } while (0)
; #define PG8_WAIT_V(n) asm volatile("s_waitcnt vmcnt(" #n ")" ::: "memory")
; #define PG8_WAIT_L(n) asm volatile("s_waitcnt lgkmcnt(" #n ")" ::: "memory")
; #define PG8_BAR __builtin_amdgcn_s_barrier()
; #define PG8_SCHED __builtin_amdgcn_sched_barrier(0)
; template <class Epi, class Sched, bool ALIGN_EPI = false, bool SP2 = false>
; __device__ __forceinline__ void gemm_phase(PG8_LAS unsigned char* lds, const Gemm g, const Sched& S, const Epi& E) {
;     ...
;             PG8_LDB(B0, 1, 0); PG8_LDB(B1, 1, 1); PG8_SCHED; PG8_LDA(At, 1, 0); PG8_STAGE(PG8_SA(0, 1), a2 + hstepA, voffA);
;             PG8_WAIT_V(8); PG8_WAIT_L(0); PG8_BAR; PG8_MMA(0, 0, At, B0); PG8_MMA(0, 1, At, B1); PG8_BAR; PG8_SCHED;
;             PG8_LDA(At, 1, 1); PG8_STAGE(PG8_SB(1, 0), b3, voffB); PG8_STAGE(PG8_SB(1, 1), b3 + hstepB, voffB); PG8_STAGE(PG8_SA(1, 0), a3, voffA);
;             PG8_WAIT_V(8); PG8_WAIT_L(0); PG8_BAR; PG8_MMA(1, 0, At, B0); PG8_MMA(1, 1, At, B1); PG8_BAR; PG8_SCHED;
	s_add_i32 s63, 0, 0x18000
	v_add_u32_e32 v155, s63, v150
	s_add_i32 s64, 0, 0x1c000
	ds_read_b128 v[144:147], v155
	ds_read_b128 v[156:159], v155 offset:1024
	ds_read_b128 v[160:163], v155 offset:2048
	ds_read_b128 v[164:167], v155 offset:3072
	v_add_u32_e32 v155, s64, v150
	ds_read_b128 v[168:171], v155
	ds_read_b128 v[172:175], v155 offset:1024
	ds_read_b128 v[176:179], v155 offset:2048
	ds_read_b128 v[180:183], v155 offset:3072
	s_mov_b64 s[100:101], s[38:39]
	s_add_u32 s38, s38, 0x80000
	s_addc_u32 s39, s39, 0
	ds_read_b128 v[184:187], v153 offset:32768
	ds_read_b128 v[188:191], v153 offset:33792
	ds_read_b128 v[192:195], v153 offset:34816
	ds_read_b128 v[196:199], v153 offset:35840
	ds_read_b128 v[200:203], v153 offset:36864
	ds_read_b128 v[204:207], v153 offset:37888
	ds_read_b128 v[208:211], v153 offset:38912
	ds_read_b128 v[212:215], v153 offset:39936
	s_mov_b32 m0, s6
	s_nop 0
	global_load_lds_dwordx4 v134, s[100:101]
	s_mov_b32 m0, s7
	s_nop 0
	global_load_lds_dwordx4 v130, s[100:101]
	s_mov_b32 m0, s41
	s_nop 0
	global_load_lds_dwordx4 v134, s[38:39]
	s_mov_b32 m0, s42
	s_nop 0
	global_load_lds_dwordx4 v130, s[38:39]
	s_waitcnt vmcnt(8)
	s_waitcnt lgkmcnt(0)
	s_barrier
	s_setprio 1
	s_waitcnt lgkmcnt(0)
	v_mfma_f32_16x16x32_bf16 v[124:127], v[144:147], v[184:187], v[124:127]
	v_mfma_f32_16x16x32_bf16 v[116:119], v[160:163], v[184:187], v[116:119]
	v_mfma_f32_16x16x32_bf16 v[108:111], v[144:147], v[192:195], v[108:111]
	v_mfma_f32_16x16x32_bf16 v[100:103], v[160:163], v[192:195], v[100:103]
	v_mfma_f32_16x16x32_bf16 v[92:95], v[144:147], v[200:203], v[92:95]
	v_mfma_f32_16x16x32_bf16 v[84:87], v[160:163], v[200:203], v[84:87]
	v_mfma_f32_16x16x32_bf16 v[76:79], v[144:147], v[208:211], v[76:79]
	v_mfma_f32_16x16x32_bf16 v[68:71], v[160:163], v[208:211], v[68:71]
	v_mfma_f32_16x16x32_bf16 v[124:127], v[156:159], v[188:191], v[124:127]
	v_mfma_f32_16x16x32_bf16 v[116:119], v[164:167], v[188:191], v[116:119]
	v_mfma_f32_16x16x32_bf16 v[108:111], v[156:159], v[196:199], v[108:111]
	v_mfma_f32_16x16x32_bf16 v[100:103], v[164:167], v[196:199], v[100:103]
	v_mfma_f32_16x16x32_bf16 v[92:95], v[156:159], v[204:207], v[92:95]
	v_mfma_f32_16x16x32_bf16 v[84:87], v[164:167], v[204:207], v[84:87]
	v_mfma_f32_16x16x32_bf16 v[76:79], v[156:159], v[212:215], v[76:79]
	v_mfma_f32_16x16x32_bf16 v[68:71], v[164:167], v[212:215], v[68:71]
	s_setprio 0
	s_setprio 1
	v_mfma_f32_16x16x32_bf16 v[120:123], v[168:171], v[184:187], v[120:123]
	v_mfma_f32_16x16x32_bf16 v[112:115], v[176:179], v[184:187], v[112:115]
	v_mfma_f32_16x16x32_bf16 v[104:107], v[168:171], v[192:195], v[104:107]
	v_mfma_f32_16x16x32_bf16 v[96:99], v[176:179], v[192:195], v[96:99]
	v_mfma_f32_16x16x32_bf16 v[88:91], v[168:171], v[200:203], v[88:91]
	v_mfma_f32_16x16x32_bf16 v[80:83], v[176:179], v[200:203], v[80:83]
	v_mfma_f32_16x16x32_bf16 v[72:75], v[168:171], v[208:211], v[72:75]
	v_mfma_f32_16x16x32_bf16 v[64:67], v[176:179], v[208:211], v[64:67]
	v_mfma_f32_16x16x32_bf16 v[120:123], v[172:175], v[188:191], v[120:123]
	v_mfma_f32_16x16x32_bf16 v[112:115], v[180:183], v[188:191], v[112:115]
	v_mfma_f32_16x16x32_bf16 v[104:107], v[172:175], v[196:199], v[104:107]
	v_mfma_f32_16x16x32_bf16 v[96:99], v[180:183], v[196:199], v[96:99]
	v_mfma_f32_16x16x32_bf16 v[88:91], v[172:175], v[204:207], v[88:91]
	v_mfma_f32_16x16x32_bf16 v[80:83], v[180:183], v[204:207], v[80:83]
	v_mfma_f32_16x16x32_bf16 v[72:75], v[172:175], v[212:215], v[72:75]
	v_mfma_f32_16x16x32_bf16 v[64:67], v[180:183], v[212:215], v[64:67]
	s_setprio 0
	s_barrier
	s_add_i32 s38, s63, s4
	s_add_u32 s98, s34, 0x80
	s_addc_u32 s99, s35, 0
	s_mov_b32 m0, s38
	ds_read_b128 v[184:187], v153 offset:49152
	ds_read_b128 v[188:191], v153 offset:50176
	ds_read_b128 v[192:195], v153 offset:51200
	ds_read_b128 v[196:199], v153 offset:52224
	ds_read_b128 v[200:203], v153 offset:53248
	ds_read_b128 v[204:207], v153 offset:54272
	ds_read_b128 v[208:211], v153 offset:55296
	ds_read_b128 v[212:215], v153 offset:56320
	global_load_lds_dwordx4 v132, s[98:99]
	s_add_i32 m0, s38, 0x2000
	s_add_u32 s34, s34, 0x80080
	s_addc_u32 s35, s35, 0
	s_add_i32 s38, s64, s4
	global_load_lds_dwordx4 v128, s[98:99]
	s_mov_b32 m0, s38
	s_nop 0
	global_load_lds_dwordx4 v132, s[34:35]
	s_add_i32 m0, s38, 0x2000
	s_nop 0
	global_load_lds_dwordx4 v128, s[34:35]
	s_waitcnt vmcnt(6)
	s_waitcnt lgkmcnt(0)
	s_barrier
	s_setprio 1
	s_waitcnt lgkmcnt(0)
	v_mfma_f32_16x16x32_bf16 v[60:63], v[144:147], v[184:187], v[60:63]
	v_mfma_f32_16x16x32_bf16 v[52:55], v[160:163], v[184:187], v[52:55]
	v_mfma_f32_16x16x32_bf16 v[44:47], v[144:147], v[192:195], v[44:47]
	v_mfma_f32_16x16x32_bf16 v[36:39], v[160:163], v[192:195], v[36:39]
	v_mfma_f32_16x16x32_bf16 v[28:31], v[144:147], v[200:203], v[28:31]
	v_mfma_f32_16x16x32_bf16 v[20:23], v[160:163], v[200:203], v[20:23]
	v_mfma_f32_16x16x32_bf16 v[12:15], v[144:147], v[208:211], v[12:15]
	v_mfma_f32_16x16x32_bf16 v[4:7], v[160:163], v[208:211], v[4:7]
	v_mfma_f32_16x16x32_bf16 v[60:63], v[156:159], v[188:191], v[60:63]
	v_mfma_f32_16x16x32_bf16 v[52:55], v[164:167], v[188:191], v[52:55]
	v_mfma_f32_16x16x32_bf16 v[44:47], v[156:159], v[196:199], v[44:47]
	v_mfma_f32_16x16x32_bf16 v[36:39], v[164:167], v[196:199], v[36:39]
	v_mfma_f32_16x16x32_bf16 v[28:31], v[156:159], v[204:207], v[28:31]
	v_mfma_f32_16x16x32_bf16 v[20:23], v[164:167], v[204:207], v[20:23]
	v_mfma_f32_16x16x32_bf16 v[12:15], v[156:159], v[212:215], v[12:15]
	v_mfma_f32_16x16x32_bf16 v[4:7], v[164:167], v[212:215], v[4:7]
	s_setprio 0
	s_setprio 1
	v_mfma_f32_16x16x32_bf16 v[56:59], v[168:171], v[184:187], v[56:59]
	v_mfma_f32_16x16x32_bf16 v[48:51], v[176:179], v[184:187], v[48:51]
	v_mfma_f32_16x16x32_bf16 v[40:43], v[168:171], v[192:195], v[40:43]
	v_mfma_f32_16x16x32_bf16 v[32:35], v[176:179], v[192:195], v[32:35]
	v_mfma_f32_16x16x32_bf16 v[24:27], v[168:171], v[200:203], v[24:27]
	v_mfma_f32_16x16x32_bf16 v[16:19], v[176:179], v[200:203], v[16:19]
	v_mfma_f32_16x16x32_bf16 v[8:11], v[168:171], v[208:211], v[8:11]
	v_mfma_f32_16x16x32_bf16 v[0:3], v[176:179], v[208:211], v[0:3]
	v_mfma_f32_16x16x32_bf16 v[56:59], v[172:175], v[188:191], v[56:59]
	v_mfma_f32_16x16x32_bf16 v[48:51], v[180:183], v[188:191], v[48:51]
	v_mfma_f32_16x16x32_bf16 v[40:43], v[172:175], v[196:199], v[40:43]
	v_mfma_f32_16x16x32_bf16 v[32:35], v[180:183], v[196:199], v[32:35]
	v_mfma_f32_16x16x32_bf16 v[24:27], v[172:175], v[204:207], v[24:27]
	v_mfma_f32_16x16x32_bf16 v[16:19], v[180:183], v[204:207], v[16:19]
	v_mfma_f32_16x16x32_bf16 v[8:11], v[172:175], v[212:215], v[8:11]
	v_mfma_f32_16x16x32_bf16 v[0:3], v[180:183], v[212:215], v[0:3]
	s_setprio 0
	s_barrier
	s_add_i32 s62, s62, 2
	s_add_u32 s30, s30, 0x100
	s_addc_u32 s31, s31, 0
	s_add_u32 s60, s60, 0x100
	s_addc_u32 s61, s61, 0
	s_cmp_gt_u32 s62, 29
	s_cbranch_scc0 .LBB0_1824

; #define PG8_STAGE(bufoff, gbase, voff) do { _Pragma("unroll") for (int _i = 0; _i < 2; ++_i) \
;         __builtin_amdgcn_global_load_lds((const unsigned*)((const char*)(gbase) + (voff)[_i]), (PG8_LAS unsigned*)(lds + (bufoff) + ldsw + _i * 8192), 16, 0, 0); } while (0)
; #define PG8_LDA(dst, b, h) do { _Pragma("unroll") for (int m = 0; m < 4; ++m) _Pragma("unroll") for (int k = 0; k < 2; ++k) dst[m][k] = *(const PG8_LAS bf16x8*)(lds + PG8_SA(b, h) + aoff + m * 2048 + k * 1024); } while (0)
; #define PG8_LDB(dst, b, h) do { _Pragma("unroll") for (int n = 0; n < 2; ++n) _Pragma("unroll") for (int k = 0; k < 2; ++k) dst[n][k] = *(const PG8_LAS bf16x8*)(lds + PG8_SB(b, h) + boff + n * 2048 + k * 1024); } while (0)
; #define PG8_MMA(ai, bj, At, Bt) do { __builtin_amdgcn_s_setprio(1); _Pragma("unroll") for (int m = 0; m < 4; ++m) _Pragma("unroll") for (int n = 0; n < 2; ++n) _Pragma("unroll") for (int k = 0; k < 2; ++k) \
;         acc[ai][bj][m][n] = __builtin_amdgcn_mfma_f32_16x16x32_bf16(Bt[n][k], At[m][k], acc[ai][bj][m][n], 0, 0, 0); __builtin_amdgcn_s_setprio(0); } while (0)
; #define PG8_WAIT_V(n) asm volatile("s_waitcnt vmcnt(" #n ")" ::: "memory")
; #define PG8_WAIT_L(n) asm volatile("s_waitcnt lgkmcnt(" #n ")" ::: "memory")
; #define PG8_BAR __builtin_amdgcn_s_barrier()
; template <class Epi, class Sched, bool ALIGN_EPI = false, bool SP2 = false>
; __device__ __forceinline__ void gemm_phase(PG8_LAS unsigned char* lds, const Gemm g, const Sched& S, const Epi& E) {
;     ...
;             const char* a1 = cA + (size_t)(t + 1) * kstep;
;             const char* a2 = last ? nA : cA + (size_t)(t + 2) * kstep; const char* b2 = last ? nB : cB + (size_t)(t + 2) * kstep;
;             const char* a3 = a2 + kstep; const char* b3 = b2 + kstep;
;             if (last && has_next) S.a_ready(nxt);
;             if constexpr (SP2) {
;             PG8_LDB(B0, 0, 0); PG8_LDB(B1, 0, 1); PG8_SCHED; PG8_LDA(At, 0, 0); PG8_STAGE(PG8_SA(1, 1), a1 + hstepA, voffA);
;             PG8_WAIT_V(8); PG8_WAIT_L(0); PG8_BAR; PG8_MMA(0, 0, At, B0); PG8_MMA(0, 1, At, B1); PG8_BAR; PG8_SCHED;
;             PG8_LDA(At, 0, 1); PG8_STAGE(PG8_SB(0, 0), b2, voffB); PG8_STAGE(PG8_SB(0, 1), b2 + hstepB, voffB); PG8_STAGE(PG8_SA(0, 0), a2, voffA);
;             PG8_WAIT_V(8); PG8_WAIT_L(0); PG8_BAR; PG8_MMA(1, 0, At, B0); PG8_MMA(1, 1, At, B1); PG8_BAR; PG8_SCHED;
.LBB0_1912:
	ds_read_b128 v[144:147], v151
	ds_read_b128 v[154:157], v151 offset:1024
	ds_read_b128 v[158:161], v151 offset:2048
	ds_read_b128 v[162:165], v151 offset:3072
	ds_read_b128 v[166:169], v152
	ds_read_b128 v[170:173], v152 offset:1024
	ds_read_b128 v[174:177], v152 offset:2048
	ds_read_b128 v[178:181], v152 offset:3072
	s_add_u32 s4, s40, 0x100
	s_addc_u32 s5, s41, 0
	s_cmpk_eq_i32 s65, 0x54
	s_cselect_b32 s47, s35, s5
	s_cselect_b32 s46, s34, s4
	s_cselect_b32 s43, s37, s64
	s_cselect_b32 s42, s36, s39
	ds_read_b128 v[182:185], v153
	ds_read_b128 v[186:189], v153 offset:1024
	ds_read_b128 v[190:193], v153 offset:2048
	ds_read_b128 v[194:197], v153 offset:3072
	ds_read_b128 v[198:201], v153 offset:4096
	ds_read_b128 v[202:205], v153 offset:5120
	ds_read_b128 v[206:209], v153 offset:6144
	ds_read_b128 v[210:213], v153 offset:7168
	s_add_u32 s98, s40, 0x80
	s_addc_u32 s99, s41, 0
	s_mov_b32 m0, s55
	s_nop 0
	global_load_lds_dwordx4 v128, s[98:99]
	s_mov_b32 m0, s56
	s_nop 0
	global_load_lds_dwordx4 v132, s[98:99]
	s_add_i32 m0, s50, 0xc000
	s_nop 0
	global_load_lds_dwordx4 v136, s[40:41]
	s_add_i32 m0, s50, 0xe000
	s_nop 0
	global_load_lds_dwordx4 v138, s[40:41]
	s_waitcnt vmcnt(8)
	s_waitcnt lgkmcnt(0)
	s_barrier
	s_setprio 1
	s_waitcnt lgkmcnt(0)
	v_mfma_f32_16x16x32_bf16 v[120:123], v[144:147], v[182:185], v[120:123]
	v_mfma_f32_16x16x32_bf16 v[124:127], v[158:161], v[182:185], v[124:127]
	v_mfma_f32_16x16x32_bf16 v[104:107], v[144:147], v[190:193], v[104:107]
	v_mfma_f32_16x16x32_bf16 v[108:111], v[158:161], v[190:193], v[108:111]
	v_mfma_f32_16x16x32_bf16 v[88:91], v[144:147], v[198:201], v[88:91]
	v_mfma_f32_16x16x32_bf16 v[92:95], v[158:161], v[198:201], v[92:95]
	v_mfma_f32_16x16x32_bf16 v[72:75], v[144:147], v[206:209], v[72:75]
	v_mfma_f32_16x16x32_bf16 v[76:79], v[158:161], v[206:209], v[76:79]
	v_mfma_f32_16x16x32_bf16 v[120:123], v[154:157], v[186:189], v[120:123]
	v_mfma_f32_16x16x32_bf16 v[124:127], v[162:165], v[186:189], v[124:127]
	v_mfma_f32_16x16x32_bf16 v[104:107], v[154:157], v[194:197], v[104:107]
	v_mfma_f32_16x16x32_bf16 v[108:111], v[162:165], v[194:197], v[108:111]
	v_mfma_f32_16x16x32_bf16 v[88:91], v[154:157], v[202:205], v[88:91]
	v_mfma_f32_16x16x32_bf16 v[92:95], v[162:165], v[202:205], v[92:95]
	v_mfma_f32_16x16x32_bf16 v[72:75], v[154:157], v[210:213], v[72:75]
	v_mfma_f32_16x16x32_bf16 v[76:79], v[162:165], v[210:213], v[76:79]
	s_setprio 0
	s_setprio 1
	v_mfma_f32_16x16x32_bf16 v[112:115], v[166:169], v[182:185], v[112:115]
	v_mfma_f32_16x16x32_bf16 v[116:119], v[174:177], v[182:185], v[116:119]
	v_mfma_f32_16x16x32_bf16 v[96:99], v[166:169], v[190:193], v[96:99]
	v_mfma_f32_16x16x32_bf16 v[100:103], v[174:177], v[190:193], v[100:103]
	v_mfma_f32_16x16x32_bf16 v[80:83], v[166:169], v[198:201], v[80:83]
	v_mfma_f32_16x16x32_bf16 v[84:87], v[174:177], v[198:201], v[84:87]
	v_mfma_f32_16x16x32_bf16 v[64:67], v[166:169], v[206:209], v[64:67]
	v_mfma_f32_16x16x32_bf16 v[68:71], v[174:177], v[206:209], v[68:71]
	v_mfma_f32_16x16x32_bf16 v[112:115], v[170:173], v[186:189], v[112:115]
	v_mfma_f32_16x16x32_bf16 v[116:119], v[178:181], v[186:189], v[116:119]
	v_mfma_f32_16x16x32_bf16 v[96:99], v[170:173], v[194:197], v[96:99]
	v_mfma_f32_16x16x32_bf16 v[100:103], v[178:181], v[194:197], v[100:103]
	v_mfma_f32_16x16x32_bf16 v[80:83], v[170:173], v[202:205], v[80:83]
	v_mfma_f32_16x16x32_bf16 v[84:87], v[178:181], v[202:205], v[84:87]
	v_mfma_f32_16x16x32_bf16 v[64:67], v[170:173], v[210:213], v[64:67]
	v_mfma_f32_16x16x32_bf16 v[68:71], v[178:181], v[210:213], v[68:71]
	s_setprio 0
	s_barrier
	s_add_i32 s40, s58, s33
	s_mov_b32 m0, s40
	ds_read_b128 v[182:185], v153 offset:16384
	ds_read_b128 v[186:189], v153 offset:17408
	ds_read_b128 v[190:193], v153 offset:18432
	ds_read_b128 v[194:197], v153 offset:19456
	ds_read_b128 v[198:201], v153 offset:20480
	ds_read_b128 v[202:205], v153 offset:21504
	ds_read_b128 v[206:209], v153 offset:22528
	ds_read_b128 v[210:213], v153 offset:23552
	global_load_lds_dwordx4 v130, s[42:43]
	s_add_i32 m0, s40, 0x2000
	s_add_u32 s40, s42, 0x160000
	s_addc_u32 s41, s43, 0
	s_add_i32 s66, s59, s33
	global_load_lds_dwordx4 v134, s[42:43]
	s_mov_b32 m0, s66
	s_nop 0
	global_load_lds_dwordx4 v130, s[40:41]
	s_add_i32 m0, s66, 0x2000
	s_nop 0
	global_load_lds_dwordx4 v134, s[40:41]
	s_waitcnt vmcnt(6)
	s_waitcnt lgkmcnt(0)
	s_barrier
	s_setprio 1
	s_waitcnt lgkmcnt(0)
	v_mfma_f32_16x16x32_bf16 v[56:59], v[144:147], v[182:185], v[56:59]
	v_mfma_f32_16x16x32_bf16 v[60:63], v[158:161], v[182:185], v[60:63]
	v_mfma_f32_16x16x32_bf16 v[40:43], v[144:147], v[190:193], v[40:43]
	v_mfma_f32_16x16x32_bf16 v[44:47], v[158:161], v[190:193], v[44:47]
	v_mfma_f32_16x16x32_bf16 v[24:27], v[144:147], v[198:201], v[24:27]
	v_mfma_f32_16x16x32_bf16 v[28:31], v[158:161], v[198:201], v[28:31]
	v_mfma_f32_16x16x32_bf16 v[8:11], v[144:147], v[206:209], v[8:11]
	v_mfma_f32_16x16x32_bf16 v[12:15], v[158:161], v[206:209], v[12:15]
	v_mfma_f32_16x16x32_bf16 v[56:59], v[154:157], v[186:189], v[56:59]
	v_mfma_f32_16x16x32_bf16 v[60:63], v[162:165], v[186:189], v[60:63]
	v_mfma_f32_16x16x32_bf16 v[40:43], v[154:157], v[194:197], v[40:43]
	v_mfma_f32_16x16x32_bf16 v[44:47], v[162:165], v[194:197], v[44:47]
	v_mfma_f32_16x16x32_bf16 v[24:27], v[154:157], v[202:205], v[24:27]
	v_mfma_f32_16x16x32_bf16 v[28:31], v[162:165], v[202:205], v[28:31]
	v_mfma_f32_16x16x32_bf16 v[8:11], v[154:157], v[210:213], v[8:11]
	v_mfma_f32_16x16x32_bf16 v[12:15], v[162:165], v[210:213], v[12:15]
	s_setprio 0
	s_setprio 1
	v_mfma_f32_16x16x32_bf16 v[48:51], v[166:169], v[182:185], v[48:51]
	v_mfma_f32_16x16x32_bf16 v[52:55], v[174:177], v[182:185], v[52:55]
	v_mfma_f32_16x16x32_bf16 v[32:35], v[166:169], v[190:193], v[32:35]
	v_mfma_f32_16x16x32_bf16 v[36:39], v[174:177], v[190:193], v[36:39]
	v_mfma_f32_16x16x32_bf16 v[16:19], v[166:169], v[198:201], v[16:19]
	v_mfma_f32_16x16x32_bf16 v[20:23], v[174:177], v[198:201], v[20:23]
	v_mfma_f32_16x16x32_bf16 v[4:7], v[166:169], v[206:209], v[4:7]
	v_mfma_f32_16x16x32_bf16 v[0:3], v[174:177], v[206:209], v[0:3]
	v_mfma_f32_16x16x32_bf16 v[48:51], v[170:173], v[186:189], v[48:51]
	v_mfma_f32_16x16x32_bf16 v[52:55], v[178:181], v[186:189], v[52:55]
	v_mfma_f32_16x16x32_bf16 v[32:35], v[170:173], v[194:197], v[32:35]
	v_mfma_f32_16x16x32_bf16 v[36:39], v[178:181], v[194:197], v[36:39]
	v_mfma_f32_16x16x32_bf16 v[16:19], v[170:173], v[202:205], v[16:19]
	v_mfma_f32_16x16x32_bf16 v[20:23], v[178:181], v[202:205], v[20:23]
	v_mfma_f32_16x16x32_bf16 v[4:7], v[170:173], v[210:213], v[4:7]
	v_mfma_f32_16x16x32_bf16 v[0:3], v[178:181], v[210:213], v[0:3]
	s_setprio 0
	s_barrier
; #define PG8_STAGE(bufoff, gbase, voff) do { _Pragma("unroll") for (int _i = 0; _i < 2; ++_i) \
;         __builtin_amdgcn_global_load_lds((const unsigned*)((const char*)(gbase) + (voff)[_i]), (PG8_LAS unsigned*)(lds + (bufoff) + ldsw + _i * 8192), 16, 0, 0); } while (0)
; #define PG8_LDA(dst, b, h) do { _Pragma("unroll") for (int m = 0; m < 4; ++m) _Pragma("unroll") for (int k = 0; k < 2; ++k) dst[m][k] = *(const PG8_LAS bf16x8*)(lds + PG8_SA(b, h) + aoff + m * 2048 + k * 1024); } while (0)
; #define PG8_LDB(dst, b, h) do { _Pragma("unroll") for (int n = 0; n < 2; ++n) _Pragma("unroll") for (int k = 0; k < 2; ++k) dst[n][k] = *(const PG8_LAS bf16x8*)(lds + PG8_SB(b, h) + boff + n * 2048 + k * 1024); } while (0)
; #define PG8_MMA(ai, bj, At, Bt) do { __builtin_amdgcn_s_setprio(1); _Pragma("unroll") for (int m = 0; m < 4; ++m) _Pragma("unroll") for (int n = 0; n < 2; ++n) _Pragma("unroll") for (int k = 0; k < 2; ++k) \
;         acc[ai][bj][m][n] = __builtin_amdgcn_mfma_f32_16x16x32_bf16(Bt[n][k], At[m][k], acc[ai][bj][m][n], 0, 0, 0); __builtin_amdgcn_s_setprio(0); } while (0)
; #define PG8_WAIT_V(n) asm volatile("s_waitcnt vmcnt(" #n ")" ::: "memory")
; #define PG8_WAIT_L(n) asm volatile("s_waitcnt lgkmcnt(" #n ")" ::: "memory")
; #define PG8_BAR __builtin_amdgcn_s_barrier()
; #define PG8_SCHED __builtin_amdgcn_sched_barrier(0)
; template <class Epi, class Sched, bool ALIGN_EPI = false, bool SP2 = false>
; __device__ __forceinline__ void gemm_phase(PG8_LAS unsigned char* lds, const Gemm g, const Sched& S, const Epi& E) {
;     ...
;             PG8_LDB(B0, 1, 0); PG8_LDB(B1, 1, 1); PG8_SCHED; PG8_LDA(At, 1, 0); PG8_STAGE(PG8_SA(0, 1), a2 + hstepA, voffA);
;             PG8_WAIT_V(8); PG8_WAIT_L(0); PG8_BAR; PG8_MMA(0, 0, At, B0); PG8_MMA(0, 1, At, B1); PG8_BAR; PG8_SCHED;
;             PG8_LDA(At, 1, 1); PG8_STAGE(PG8_SB(1, 0), b3, voffB); PG8_STAGE(PG8_SB(1, 1), b3 + hstepB, voffB); PG8_STAGE(PG8_SA(1, 0), a3, voffA);
;             PG8_WAIT_V(8); PG8_WAIT_L(0); PG8_BAR; PG8_MMA(1, 0, At, B0); PG8_MMA(1, 1, At, B1); PG8_BAR; PG8_SCHED;
	s_add_i32 s66, 0, 0x18000
	s_add_i32 s67, 0, 0x1c000
	v_add_u32_e32 v162, s66, v150
	v_add_u32_e32 v178, s67, v150
	ds_read_b128 v[144:147], v162
	ds_read_b128 v[154:157], v162 offset:1024
	ds_read_b128 v[158:161], v162 offset:2048
	ds_read_b128 v[162:165], v162 offset:3072
	ds_read_b128 v[166:169], v178
	ds_read_b128 v[170:173], v178 offset:1024
	ds_read_b128 v[174:177], v178 offset:2048
	ds_read_b128 v[178:181], v178 offset:3072
	s_add_u32 s40, s46, 0x160000
	s_addc_u32 s41, s47, 0
	ds_read_b128 v[182:185], v153 offset:32768
	ds_read_b128 v[186:189], v153 offset:33792
	ds_read_b128 v[190:193], v153 offset:34816
	ds_read_b128 v[194:197], v153 offset:35840
	ds_read_b128 v[198:201], v153 offset:36864
	ds_read_b128 v[202:205], v153 offset:37888
	ds_read_b128 v[206:209], v153 offset:38912
	ds_read_b128 v[210:213], v153 offset:39936
	s_mov_b32 m0, s50
	s_nop 0
	global_load_lds_dwordx4 v128, s[46:47]
	s_mov_b32 m0, s51
	s_nop 0
	global_load_lds_dwordx4 v132, s[46:47]
	s_mov_b32 m0, s52
	s_nop 0
	global_load_lds_dwordx4 v128, s[40:41]
	s_mov_b32 m0, s53
	s_nop 0
	global_load_lds_dwordx4 v132, s[40:41]
	s_waitcnt vmcnt(8)
	s_waitcnt lgkmcnt(0)
	s_barrier
	s_setprio 1
	s_waitcnt lgkmcnt(0)
	v_mfma_f32_16x16x32_bf16 v[120:123], v[144:147], v[182:185], v[120:123]
	v_mfma_f32_16x16x32_bf16 v[124:127], v[158:161], v[182:185], v[124:127]
	v_mfma_f32_16x16x32_bf16 v[104:107], v[144:147], v[190:193], v[104:107]
	v_mfma_f32_16x16x32_bf16 v[108:111], v[158:161], v[190:193], v[108:111]
	v_mfma_f32_16x16x32_bf16 v[88:91], v[144:147], v[198:201], v[88:91]
	v_mfma_f32_16x16x32_bf16 v[92:95], v[158:161], v[198:201], v[92:95]
	v_mfma_f32_16x16x32_bf16 v[72:75], v[144:147], v[206:209], v[72:75]
	v_mfma_f32_16x16x32_bf16 v[76:79], v[158:161], v[206:209], v[76:79]
	v_mfma_f32_16x16x32_bf16 v[120:123], v[154:157], v[186:189], v[120:123]
	v_mfma_f32_16x16x32_bf16 v[124:127], v[162:165], v[186:189], v[124:127]
	v_mfma_f32_16x16x32_bf16 v[104:107], v[154:157], v[194:197], v[104:107]
	v_mfma_f32_16x16x32_bf16 v[108:111], v[162:165], v[194:197], v[108:111]
	v_mfma_f32_16x16x32_bf16 v[88:91], v[154:157], v[202:205], v[88:91]
	v_mfma_f32_16x16x32_bf16 v[92:95], v[162:165], v[202:205], v[92:95]
	v_mfma_f32_16x16x32_bf16 v[72:75], v[154:157], v[210:213], v[72:75]
	v_mfma_f32_16x16x32_bf16 v[76:79], v[162:165], v[210:213], v[76:79]
	s_setprio 0
	s_setprio 1
	v_mfma_f32_16x16x32_bf16 v[112:115], v[166:169], v[182:185], v[112:115]
	v_mfma_f32_16x16x32_bf16 v[116:119], v[174:177], v[182:185], v[116:119]
	v_mfma_f32_16x16x32_bf16 v[96:99], v[166:169], v[190:193], v[96:99]
	v_mfma_f32_16x16x32_bf16 v[100:103], v[174:177], v[190:193], v[100:103]
	v_mfma_f32_16x16x32_bf16 v[80:83], v[166:169], v[198:201], v[80:83]
	v_mfma_f32_16x16x32_bf16 v[84:87], v[174:177], v[198:201], v[84:87]
	v_mfma_f32_16x16x32_bf16 v[64:67], v[166:169], v[206:209], v[64:67]
	v_mfma_f32_16x16x32_bf16 v[68:71], v[174:177], v[206:209], v[68:71]
	v_mfma_f32_16x16x32_bf16 v[112:115], v[170:173], v[186:189], v[112:115]
	v_mfma_f32_16x16x32_bf16 v[116:119], v[178:181], v[186:189], v[116:119]
	v_mfma_f32_16x16x32_bf16 v[96:99], v[170:173], v[194:197], v[96:99]
	v_mfma_f32_16x16x32_bf16 v[100:103], v[178:181], v[194:197], v[100:103]
	v_mfma_f32_16x16x32_bf16 v[80:83], v[170:173], v[202:205], v[80:83]
	v_mfma_f32_16x16x32_bf16 v[84:87], v[178:181], v[202:205], v[84:87]
	v_mfma_f32_16x16x32_bf16 v[64:67], v[170:173], v[210:213], v[64:67]
	v_mfma_f32_16x16x32_bf16 v[68:71], v[178:181], v[210:213], v[68:71]
	s_setprio 0
	s_barrier
	s_add_i32 s40, s66, s33
	s_add_u32 s98, s42, 0x80
	s_addc_u32 s99, s43, 0
	s_mov_b32 m0, s40
	ds_read_b128 v[182:185], v153 offset:49152
	ds_read_b128 v[186:189], v153 offset:50176
	ds_read_b128 v[190:193], v153 offset:51200
	ds_read_b128 v[194:197], v153 offset:52224
	ds_read_b128 v[198:201], v153 offset:53248
	ds_read_b128 v[202:205], v153 offset:54272
	ds_read_b128 v[206:209], v153 offset:55296
	ds_read_b128 v[210:213], v153 offset:56320
	global_load_lds_dwordx4 v130, s[98:99]
	s_add_i32 m0, s40, 0x2000
	s_add_u32 s40, s42, 0x160080
	s_addc_u32 s41, s43, 0
	s_add_i32 s42, s67, s33
	global_load_lds_dwordx4 v134, s[98:99]
	s_mov_b32 m0, s42
	s_nop 0
	global_load_lds_dwordx4 v130, s[40:41]
	s_add_i32 m0, s42, 0x2000
	s_nop 0
	global_load_lds_dwordx4 v134, s[40:41]
	s_waitcnt vmcnt(6)
	s_waitcnt lgkmcnt(0)
	s_barrier
	s_setprio 1
	s_waitcnt lgkmcnt(0)
	v_mfma_f32_16x16x32_bf16 v[56:59], v[144:147], v[182:185], v[56:59]
	v_mfma_f32_16x16x32_bf16 v[60:63], v[158:161], v[182:185], v[60:63]
	v_mfma_f32_16x16x32_bf16 v[40:43], v[144:147], v[190:193], v[40:43]
	v_mfma_f32_16x16x32_bf16 v[44:47], v[158:161], v[190:193], v[44:47]
	v_mfma_f32_16x16x32_bf16 v[24:27], v[144:147], v[198:201], v[24:27]
	v_mfma_f32_16x16x32_bf16 v[28:31], v[158:161], v[198:201], v[28:31]
	v_mfma_f32_16x16x32_bf16 v[8:11], v[144:147], v[206:209], v[8:11]
	v_mfma_f32_16x16x32_bf16 v[12:15], v[158:161], v[206:209], v[12:15]
	v_mfma_f32_16x16x32_bf16 v[56:59], v[154:157], v[186:189], v[56:59]
	v_mfma_f32_16x16x32_bf16 v[60:63], v[162:165], v[186:189], v[60:63]
	v_mfma_f32_16x16x32_bf16 v[40:43], v[154:157], v[194:197], v[40:43]
	v_mfma_f32_16x16x32_bf16 v[44:47], v[162:165], v[194:197], v[44:47]
	v_mfma_f32_16x16x32_bf16 v[24:27], v[154:157], v[202:205], v[24:27]
	v_mfma_f32_16x16x32_bf16 v[28:31], v[162:165], v[202:205], v[28:31]
	v_mfma_f32_16x16x32_bf16 v[8:11], v[154:157], v[210:213], v[8:11]
	v_mfma_f32_16x16x32_bf16 v[12:15], v[162:165], v[210:213], v[12:15]
	s_setprio 0
	s_setprio 1
	v_mfma_f32_16x16x32_bf16 v[48:51], v[166:169], v[182:185], v[48:51]
	v_mfma_f32_16x16x32_bf16 v[52:55], v[174:177], v[182:185], v[52:55]
	v_mfma_f32_16x16x32_bf16 v[32:35], v[166:169], v[190:193], v[32:35]
	v_mfma_f32_16x16x32_bf16 v[36:39], v[174:177], v[190:193], v[36:39]
	v_mfma_f32_16x16x32_bf16 v[16:19], v[166:169], v[198:201], v[16:19]
	v_mfma_f32_16x16x32_bf16 v[20:23], v[174:177], v[198:201], v[20:23]
	v_mfma_f32_16x16x32_bf16 v[4:7], v[166:169], v[206:209], v[4:7]
	v_mfma_f32_16x16x32_bf16 v[0:3], v[174:177], v[206:209], v[0:3]
	v_mfma_f32_16x16x32_bf16 v[48:51], v[170:173], v[186:189], v[48:51]
	v_mfma_f32_16x16x32_bf16 v[52:55], v[178:181], v[186:189], v[52:55]
	v_mfma_f32_16x16x32_bf16 v[32:35], v[170:173], v[194:197], v[32:35]
	v_mfma_f32_16x16x32_bf16 v[36:39], v[178:181], v[194:197], v[36:39]
	v_mfma_f32_16x16x32_bf16 v[16:19], v[170:173], v[202:205], v[16:19]
	v_mfma_f32_16x16x32_bf16 v[20:23], v[178:181], v[202:205], v[20:23]
	v_mfma_f32_16x16x32_bf16 v[4:7], v[170:173], v[210:213], v[4:7]
	v_mfma_f32_16x16x32_bf16 v[0:3], v[178:181], v[210:213], v[0:3]
	s_setprio 0
	s_barrier
	s_add_i32 s65, s65, 2
	s_add_u32 s39, s39, 0x100
	s_addc_u32 s64, s64, 0
	s_cmpk_gt_u32 s65, 0x55
	s_mov_b64 s[40:41], s[4:5]
	s_cbranch_scc0 .LBB0_1912
	s_and_b64 vcc, exec, s[14:15]
	s_cbranch_vccz .LBB0_1915
	s_barrier
